# P1a->attention seam split in two stages (rounds 0-3 for dilation groups 0,1 waited at attention start; round 4 waited before the first group-2 item)
# speedup vs baseline: 1.0113x; 1.0028x over previous
.LBB0_447:
	s_cmp_lt_i32 s78, 5
	s_cselect_b64 s[2:3], -1, 0
	s_and_b64 s[2:3], s[2:3], s[0:1]
	s_andn2_b64 vcc, exec, s[2:3]
	s_cbranch_vccnz .LBB0_469
	s_mov_b32 s87, 0
	s_mov_b32 s32, 0
	s_mov_b32 s85, 0
	s_cmpk_gt_i32 s74, 0x47f
	v_readfirstlane_b32 s1, v171
	s_cbranch_scc1 .LBB0_464
	v_lshrrev_b32_e32 v2, 1, v171
	v_and_b32_e32 v11, 24, v2
	v_lshrrev_b32_e32 v2, 5, v171
	v_and_b32_e32 v2, 4, v2
	v_bfe_u32 v3, v171, 2, 2
	v_lshlrev_b32_e32 v0, 4, v171
	v_and_b32_e32 v1, 32, v171
	v_bfe_u32 v10, v171, 2, 4
	v_or3_b32 v2, v2, v3, v11
	v_lshrrev_b32_e32 v3, 3, v171
	s_movk_i32 s0, 0x70
	v_bitop3_b32 v8, v0, v1, 48 bitop3:0x6c
	v_and_b32_e32 v9, 64, v171
	v_and_or_b32 v4, v3, s0, v10
	s_movk_i32 s0, 0x60
	v_add_u32_e32 v12, 0x2000, v0
	v_or_b32_e32 v1, v8, v9
	v_and_or_b32 v3, v3, s0, v2
	v_lshrrev_b32_e32 v0, 7, v12
	s_movk_i32 s0, 0xf0
	v_lshl_or_b32 v130, v3, 11, v1
	v_and_or_b32 v3, v0, s0, v10
	s_movk_i32 s0, 0xe0
	s_ashr_i32 s27, s74, 31
	v_and_or_b32 v0, v0, s0, v2
	s_lshr_b32 s0, s27, 29
	s_add_i32 s0, s74, s0
	s_lshr_b32 s6, s1, 6
	s_ashr_i32 s4, s0, 3
	s_and_b32 s0, s0, -8
	s_lshr_b32 s8, s1, 8
	s_lshl_b32 s26, s6, 10
	s_sub_i32 s0, s74, s0
	s_cmp_lt_i32 s0, 0
	s_movk_i32 s28, 0x91
	s_cselect_b32 s5, s28, 0x90
	s_mul_i32 s0, s0, s5
	s_add_i32 s0, s0, s4
	s_mul_hi_i32 s4, s0, 0x38e38e39
	s_lshr_b32 s5, s4, 31
	s_ashr_i32 s4, s4, 5
	s_add_i32 s4, s4, s5
	s_lshl_b32 s5, s4, 3
	s_mulk_i32 s4, 0x90
	s_sub_i32 s4, s0, s4
	s_sext_i32_i16 s0, s4
	s_bfe_u32 s0, s0, 0x3001c
	s_add_i32 s7, s4, s0
	s_sext_i32_i16 s0, s7
	s_and_b32 s7, s7, 0xfff8
	s_sub_i32 s4, s4, s7
	s_sext_i32_i16 s4, s4
	s_lshr_b32 s0, s0, 3
	s_add_i32 s18, s5, s4
	s_ashr_i32 s19, s18, 31
	s_bfe_i64 s[10:11], s[0:1], 0x100000
	s_lshl_b64 s[4:5], s[18:19], 19
	s_lshl_b64 s[10:11], s[10:11], 19
	v_readlane_b32 s12, v246, 36
	v_readlane_b32 s13, v246, 37
	s_add_u32 s22, s12, s10
	s_addc_u32 s23, s13, s11
	s_add_i32 s19, s26, 0
	s_add_i32 m0, s19, 0x10000
	v_lshl_or_b32 v134, v0, 11, v1
	global_load_lds_dwordx4 v130, s[22:23]
	s_add_i32 m0, s19, 0x12000
	s_add_u32 s10, s22, 0x40000
	global_load_lds_dwordx4 v134, s[22:23]
	s_addc_u32 s11, s23, 0
	s_add_i32 m0, s19, 0x14000
	v_readlane_b32 s36, v246, 20
	global_load_lds_dwordx4 v130, s[10:11]
	s_add_i32 m0, s19, 0x16000
	v_readlane_b32 s50, v246, 34
	v_readlane_b32 s51, v246, 35
	s_add_u32 s20, s50, s4
	s_addc_u32 s21, s51, s5
	s_add_i32 s29, s19, 0x2000
	v_lshl_or_b32 v128, v4, 11, v1
	global_load_lds_dwordx4 v134, s[10:11]
	s_mov_b32 m0, s19
	s_add_u32 s4, s20, 0x40000
	v_lshl_or_b32 v132, v3, 11, v1
	global_load_lds_dwordx4 v128, s[20:21]
	s_mov_b32 m0, s29
	s_addc_u32 s5, s21, 0
	s_add_i32 s30, s19, 0x4000
	global_load_lds_dwordx4 v132, s[20:21]
	s_mov_b32 m0, s30
	s_add_i32 s31, s19, 0x6000
	global_load_lds_dwordx4 v128, s[4:5]
	s_mov_b32 m0, s31
	v_mov_b32_e32 v131, 0
	global_load_lds_dwordx4 v132, s[4:5]
	v_mov_b32_e32 v135, v131
	v_mov_b32_e32 v129, v131
	v_mov_b32_e32 v133, v131
	s_cmp_eq_u32 s8, 1
	s_mov_b32 s33, 0
	v_lshl_add_u64 v[6:7], s[22:23], 0, v[130:131]
	v_lshl_add_u64 v[4:5], s[22:23], 0, v[134:135]
	v_lshl_add_u64 v[0:1], s[20:21], 0, v[128:129]
	s_cselect_b64 s[4:5], -1, 0
	s_cmp_lg_u32 s8, 1
	v_lshl_add_u64 v[2:3], s[20:21], 0, v[132:133]
	v_readlane_b32 s37, v246, 21
	v_readlane_b32 s38, v246, 22
	v_readlane_b32 s39, v246, 23
	v_readlane_b32 s40, v246, 24
	v_readlane_b32 s41, v246, 25
	v_readlane_b32 s42, v246, 26
	v_readlane_b32 s43, v246, 27
	v_readlane_b32 s44, v246, 28
	v_readlane_b32 s45, v246, 29
	v_readlane_b32 s46, v246, 30
	v_readlane_b32 s47, v246, 31
	v_readlane_b32 s48, v246, 32
	v_readlane_b32 s49, v246, 33
	s_cbranch_scc1 .LBB0_451
	s_barrier

.Ldf3_wd:
	s_mul_hi_i32 s11, s41, 0x2aaaaaab
	s_lshr_b32 s13, s11, 31
	s_add_i32 s11, s11, s13
	s_mul_i32 s13, s11, -6
	s_add_i32 s13, s13, s41
	s_add_i32 s20, s41, 5
	s_cmp_lt_u32 s20, 11
	s_mul_hi_i32 s21, s11, 0x3000000
	s_mul_i32 s11, s11, 0x3000000
	s_cselect_b64 vcc, -1, 0
	s_add_u32 s20, s94, s11
	v_lshl_or_b32 v152, s13, 8, v147
	v_cndmask_b32_e32 v144, 1.0, v151, vcc
	s_addc_u32 s21, s95, s21
	v_ashrrev_i32_e32 v153, 31, v152
	v_lshl_add_u32 v158, s18, 8, v145
	v_lshl_add_u64 v[152:153], v[152:153], 1, s[20:21]
	v_pk_mul_f32 v[126:127], v[144:145], v[126:127] op_sel_hi:[0,1]
	v_pk_mul_f32 v[124:125], v[144:145], v[124:125] op_sel_hi:[0,1]
	v_pk_mul_f32 v[156:157], v[144:145], v[122:123] op_sel_hi:[0,1]
	v_pk_mul_f32 v[122:123], v[144:145], v[120:121] op_sel_hi:[0,1]
	v_mad_i64_i32 v[154:155], s[20:21], v158, s40, v[152:153]
	v_cvt_pk_bf16_f32 v120, v124, v125
	v_cvt_pk_bf16_f32 v121, v126, v127
	v_cvt_pk_bf16_f32 v122, v122, v123
	v_cvt_pk_bf16_f32 v123, v156, v157
	global_store_dwordx4 v[154:155], v[120:123], off
	v_pk_mul_f32 v[114:115], v[144:145], v[114:115] op_sel_hi:[0,1]
	v_pk_mul_f32 v[112:113], v[144:145], v[112:113] op_sel_hi:[0,1]
	v_pk_mul_f32 v[120:121], v[144:145], v[106:107] op_sel_hi:[0,1]
	v_pk_mul_f32 v[106:107], v[144:145], v[104:105] op_sel_hi:[0,1]
	v_cvt_pk_bf16_f32 v104, v112, v113
	v_cvt_pk_bf16_f32 v105, v114, v115
	v_cvt_pk_bf16_f32 v106, v106, v107
	v_cvt_pk_bf16_f32 v107, v120, v121
	global_store_dwordx4 v[154:155], v[104:107], off offset:256
	v_pk_mul_f32 v[110:111], v[144:145], v[110:111] op_sel_hi:[0,1]
	v_pk_mul_f32 v[108:109], v[144:145], v[108:109] op_sel_hi:[0,1]
	v_or_b32_e32 v104, 16, v158
	v_mad_i64_i32 v[112:113], s[20:21], v104, s40, v[152:153]
	v_pk_mul_f32 v[106:107], v[144:145], v[118:119] op_sel_hi:[0,1]
	v_pk_mul_f32 v[104:105], v[144:145], v[116:117] op_sel_hi:[0,1]
	v_cvt_pk_bf16_f32 v104, v104, v105
	v_cvt_pk_bf16_f32 v105, v106, v107
	v_cvt_pk_bf16_f32 v106, v108, v109
	v_cvt_pk_bf16_f32 v107, v110, v111
	global_store_dwordx4 v[112:113], v[104:107], off
	v_pk_mul_f32 v[98:99], v[144:145], v[98:99] op_sel_hi:[0,1]
	v_pk_mul_f32 v[96:97], v[144:145], v[96:97] op_sel_hi:[0,1]
	v_pk_mul_f32 v[104:105], v[144:145], v[90:91] op_sel_hi:[0,1]
	v_pk_mul_f32 v[90:91], v[144:145], v[88:89] op_sel_hi:[0,1]
	v_cvt_pk_bf16_f32 v88, v96, v97
	v_cvt_pk_bf16_f32 v89, v98, v99
	v_cvt_pk_bf16_f32 v90, v90, v91
	v_cvt_pk_bf16_f32 v91, v104, v105
	global_store_dwordx4 v[112:113], v[88:91], off offset:256
	v_pk_mul_f32 v[94:95], v[144:145], v[94:95] op_sel_hi:[0,1]
	v_pk_mul_f32 v[92:93], v[144:145], v[92:93] op_sel_hi:[0,1]
	v_or_b32_e32 v88, 32, v158
	v_mad_i64_i32 v[96:97], s[20:21], v88, s40, v[152:153]
	v_pk_mul_f32 v[90:91], v[144:145], v[102:103] op_sel_hi:[0,1]
	v_pk_mul_f32 v[88:89], v[144:145], v[100:101] op_sel_hi:[0,1]
	v_cvt_pk_bf16_f32 v88, v88, v89
	v_cvt_pk_bf16_f32 v89, v90, v91
	v_cvt_pk_bf16_f32 v90, v92, v93
	v_cvt_pk_bf16_f32 v91, v94, v95
	global_store_dwordx4 v[96:97], v[88:91], off
	v_pk_mul_f32 v[82:83], v[144:145], v[82:83] op_sel_hi:[0,1]
	v_pk_mul_f32 v[80:81], v[144:145], v[80:81] op_sel_hi:[0,1]
	v_pk_mul_f32 v[88:89], v[144:145], v[74:75] op_sel_hi:[0,1]
	v_pk_mul_f32 v[74:75], v[144:145], v[72:73] op_sel_hi:[0,1]
	v_cvt_pk_bf16_f32 v72, v80, v81
	v_cvt_pk_bf16_f32 v73, v82, v83
	v_cvt_pk_bf16_f32 v74, v74, v75
	v_cvt_pk_bf16_f32 v75, v88, v89
	global_store_dwordx4 v[96:97], v[72:75], off offset:256
	v_pk_mul_f32 v[78:79], v[144:145], v[78:79] op_sel_hi:[0,1]
	v_pk_mul_f32 v[76:77], v[144:145], v[76:77] op_sel_hi:[0,1]
	v_or_b32_e32 v72, 48, v158
	v_mad_i64_i32 v[80:81], s[20:21], v72, s40, v[152:153]
	v_pk_mul_f32 v[74:75], v[144:145], v[86:87] op_sel_hi:[0,1]
	v_pk_mul_f32 v[72:73], v[144:145], v[84:85] op_sel_hi:[0,1]
	v_cvt_pk_bf16_f32 v72, v72, v73
	v_cvt_pk_bf16_f32 v73, v74, v75
	v_cvt_pk_bf16_f32 v74, v76, v77
	v_cvt_pk_bf16_f32 v75, v78, v79
	global_store_dwordx4 v[80:81], v[72:75], off
	v_pk_mul_f32 v[70:71], v[144:145], v[70:71] op_sel_hi:[0,1]
	v_pk_mul_f32 v[68:69], v[144:145], v[68:69] op_sel_hi:[0,1]
	v_pk_mul_f32 v[72:73], v[144:145], v[66:67] op_sel_hi:[0,1]
	v_pk_mul_f32 v[66:67], v[144:145], v[64:65] op_sel_hi:[0,1]
	v_cvt_pk_bf16_f32 v64, v68, v69
	v_cvt_pk_bf16_f32 v65, v70, v71
	v_cvt_pk_bf16_f32 v66, v66, v67
	v_cvt_pk_bf16_f32 v67, v72, v73
	global_store_dwordx4 v[80:81], v[64:67], off offset:256
	v_pk_mul_f32 v[62:63], v[144:145], v[62:63] op_sel_hi:[0,1]
	v_pk_mul_f32 v[60:61], v[144:145], v[60:61] op_sel_hi:[0,1]
	v_add_u32_e32 v64, 0x80, v158
	v_pk_mul_f32 v[66:67], v[144:145], v[58:59] op_sel_hi:[0,1]
	v_pk_mul_f32 v[58:59], v[144:145], v[56:57] op_sel_hi:[0,1]
	v_mad_i64_i32 v[64:65], s[20:21], v64, s40, v[152:153]
	v_cvt_pk_bf16_f32 v56, v60, v61
	v_cvt_pk_bf16_f32 v57, v62, v63
	v_cvt_pk_bf16_f32 v58, v58, v59
	v_cvt_pk_bf16_f32 v59, v66, v67
	global_store_dwordx4 v[64:65], v[56:59], off
	v_pk_mul_f32 v[50:51], v[144:145], v[50:51] op_sel_hi:[0,1]
	v_pk_mul_f32 v[48:49], v[144:145], v[48:49] op_sel_hi:[0,1]
	v_pk_mul_f32 v[56:57], v[144:145], v[42:43] op_sel_hi:[0,1]
	v_pk_mul_f32 v[42:43], v[144:145], v[40:41] op_sel_hi:[0,1]
	v_cvt_pk_bf16_f32 v40, v48, v49
	v_cvt_pk_bf16_f32 v41, v50, v51
	v_cvt_pk_bf16_f32 v42, v42, v43
	v_cvt_pk_bf16_f32 v43, v56, v57
	global_store_dwordx4 v[64:65], v[40:43], off offset:256
	v_pk_mul_f32 v[46:47], v[144:145], v[46:47] op_sel_hi:[0,1]
	v_pk_mul_f32 v[44:45], v[144:145], v[44:45] op_sel_hi:[0,1]
	v_add_u32_e32 v40, 0x90, v158
	v_mad_i64_i32 v[48:49], s[20:21], v40, s40, v[152:153]
	v_pk_mul_f32 v[42:43], v[144:145], v[54:55] op_sel_hi:[0,1]
	v_pk_mul_f32 v[40:41], v[144:145], v[52:53] op_sel_hi:[0,1]
	v_cvt_pk_bf16_f32 v40, v40, v41
	v_cvt_pk_bf16_f32 v41, v42, v43
	v_cvt_pk_bf16_f32 v42, v44, v45
	v_cvt_pk_bf16_f32 v43, v46, v47
	global_store_dwordx4 v[48:49], v[40:43], off
	v_pk_mul_f32 v[34:35], v[144:145], v[34:35] op_sel_hi:[0,1]
	v_pk_mul_f32 v[32:33], v[144:145], v[32:33] op_sel_hi:[0,1]
	v_pk_mul_f32 v[40:41], v[144:145], v[26:27] op_sel_hi:[0,1]
	v_pk_mul_f32 v[26:27], v[144:145], v[24:25] op_sel_hi:[0,1]
	v_cvt_pk_bf16_f32 v24, v32, v33
	v_cvt_pk_bf16_f32 v25, v34, v35
	v_cvt_pk_bf16_f32 v26, v26, v27
	v_cvt_pk_bf16_f32 v27, v40, v41
	global_store_dwordx4 v[48:49], v[24:27], off offset:256
	v_pk_mul_f32 v[30:31], v[144:145], v[30:31] op_sel_hi:[0,1]
	v_pk_mul_f32 v[28:29], v[144:145], v[28:29] op_sel_hi:[0,1]
	v_add_u32_e32 v24, 0xa0, v158
	v_mad_i64_i32 v[32:33], s[20:21], v24, s40, v[152:153]
	v_pk_mul_f32 v[26:27], v[144:145], v[38:39] op_sel_hi:[0,1]
	v_pk_mul_f32 v[24:25], v[144:145], v[36:37] op_sel_hi:[0,1]
	v_cvt_pk_bf16_f32 v24, v24, v25
	v_cvt_pk_bf16_f32 v25, v26, v27
	v_cvt_pk_bf16_f32 v26, v28, v29
	v_cvt_pk_bf16_f32 v27, v30, v31
	global_store_dwordx4 v[32:33], v[24:27], off
	v_pk_mul_f32 v[18:19], v[144:145], v[18:19] op_sel_hi:[0,1]
	v_pk_mul_f32 v[16:17], v[144:145], v[16:17] op_sel_hi:[0,1]
	v_pk_mul_f32 v[24:25], v[144:145], v[10:11] op_sel_hi:[0,1]
	v_pk_mul_f32 v[10:11], v[144:145], v[8:9] op_sel_hi:[0,1]
	v_cvt_pk_bf16_f32 v8, v16, v17
	v_cvt_pk_bf16_f32 v9, v18, v19
	v_cvt_pk_bf16_f32 v10, v10, v11
	v_cvt_pk_bf16_f32 v11, v24, v25
	global_store_dwordx4 v[32:33], v[8:11], off offset:256
	v_pk_mul_f32 v[14:15], v[144:145], v[14:15] op_sel_hi:[0,1]
	v_pk_mul_f32 v[12:13], v[144:145], v[12:13] op_sel_hi:[0,1]
	v_add_u32_e32 v8, 0xb0, v158
	v_mad_i64_i32 v[16:17], s[20:21], v8, s40, v[152:153]
	v_pk_mul_f32 v[10:11], v[144:145], v[22:23] op_sel_hi:[0,1]
	v_pk_mul_f32 v[8:9], v[144:145], v[20:21] op_sel_hi:[0,1]
	v_cvt_pk_bf16_f32 v8, v8, v9
	v_cvt_pk_bf16_f32 v9, v10, v11
	v_cvt_pk_bf16_f32 v10, v12, v13
	v_cvt_pk_bf16_f32 v11, v14, v15
	global_store_dwordx4 v[16:17], v[8:11], off
	v_pk_mul_f32 v[6:7], v[144:145], v[6:7] op_sel_hi:[0,1]
	v_pk_mul_f32 v[4:5], v[144:145], v[4:5] op_sel_hi:[0,1]
	v_pk_mul_f32 v[8:9], v[144:145], v[2:3] op_sel_hi:[0,1]
	v_pk_mul_f32 v[2:3], v[144:145], v[0:1] op_sel_hi:[0,1]
	v_cvt_pk_bf16_f32 v0, v4, v5
	v_cvt_pk_bf16_f32 v1, v6, v7
	v_cvt_pk_bf16_f32 v2, v2, v3
	v_cvt_pk_bf16_f32 v3, v8, v9
	s_andn2_b64 vcc, exec, s[0:1]
	s_mov_b64 s[0:1], -1
	global_store_dwordx4 v[16:17], v[0:3], off offset:256
	s_mov_b64 s[52:53], vcc
	s_add_i32 s87, s87, 1
	s_cmp_eq_u32 s87, 4
	s_cbranch_scc0 .Ldf4a_skip
	s_and_b64 vcc, exec, s[92:93]
	s_cbranch_vccz .Ldf4a_skip
	s_waitcnt vmcnt(0)
	s_barrier
	s_mov_b32 s32, 1
	v_cmp_eq_u32_e32 vcc, 0, v171
	s_and_saveexec_b64 s[98:99], vcc
	s_cbranch_execz .Ldf4a_arr
	v_mov_b32_e32 v247, 0x20000
	ds_read_b32 v248, v247
	v_readlane_b32 s96, v246, 1
	v_readlane_b32 s97, v246, 2
	v_readlane_b32 s101, v246, 3
	s_lshl_b32 s101, s101, 2
	s_addk_i32 s101, 0x3a80
	v_mov_b32_e32 v249, s101
	v_mov_b32_e32 v250, 1
	s_nop 2
	global_atomic_add v251, v249, v250, s[96:97] sc0
	s_waitcnt vmcnt(0) lgkmcnt(0)
	v_add_u32_e32 v251, 1, v251
	v_cmp_eq_u32_e32 vcc, v251, v248
	s_cbranch_vccz .Ldf4a_arr
	buffer_wbl2 sc1
	s_waitcnt vmcnt(0)
	v_mov_b32_e32 v249, 0x3ac0
	global_atomic_add v249, v250, s[96:97]

.Ldf4a_skip:
	s_mov_b64 vcc, s[52:53]
	s_cbranch_vccnz .LBB0_453
	s_andn2_b64 vcc, exec, s[4:5]
	s_cbranch_vccnz .LBB0_452
	s_barrier
	s_branch .LBB0_452

.LBB0_469:
	s_cmp_gt_i32 s79, 5
	s_cselect_b64 s[0:1], -1, 0
	s_and_b64 s[2:3], s[2:3], s[0:1]
	s_andn2_b64 vcc, exec, s[2:3]
	s_cbranch_vccnz .LBB0_519
	s_cmp_eq_u32 s32, 1
	s_cbranch_scc0 .Ldf4_orig
	s_waitcnt vmcnt(0)
	s_barrier
	s_mov_b32 s85, 1
	v_cmp_eq_u32_e32 vcc, 0, v171
	s_and_saveexec_b64 s[98:99], vcc
	s_cbranch_execz .Ldf4b_arr
	v_mov_b32_e32 v247, 0x20000
	ds_read_b32 v248, v247
	v_readlane_b32 s96, v246, 1
	v_readlane_b32 s97, v246, 2
	v_readlane_b32 s101, v246, 3
	s_lshl_b32 s101, s101, 2
	s_addk_i32 s101, 0x3b00
	v_mov_b32_e32 v249, s101
	v_mov_b32_e32 v250, 1
	s_nop 2
	global_atomic_add v251, v249, v250, s[96:97] sc0
	s_waitcnt vmcnt(0) lgkmcnt(0)
	v_add_u32_e32 v251, 1, v251
	v_cmp_eq_u32_e32 vcc, v251, v248
	s_cbranch_vccz .Ldf4b_arr
	buffer_wbl2 sc1
	s_waitcnt vmcnt(0)
	v_mov_b32_e32 v249, 0x3b40
	global_atomic_add v249, v250, s[96:97]
.Ldf4b_arr:
	s_or_b64 exec, exec, s[98:99]
	s_cmp_eq_u32 s32, 1
	s_cbranch_scc0 .Ldf4a_wd
	s_mov_b32 s32, 0
	v_cmp_eq_u32_e64 s[98:99], 0, v171
	s_nop 1
	s_and_saveexec_b64 s[98:99], s[98:99]
	s_cbranch_execz .Ldf4a_wj
	v_mov_b32_e32 v247, 0x20004
	ds_read_b32 v248, v247
	v_readlane_b32 s96, v246, 1
	v_readlane_b32 s97, v246, 2
	v_mov_b32_e32 v249, 0x3ac0
	s_mov_b32 s90, 0
	s_waitcnt lgkmcnt(0)
	v_readfirstlane_b32 s101, v248
	s_nop 3

.Ldf4a_wd:
	s_branch .LBB0_519
.Ldf4_orig:
	s_waitcnt vmcnt(0)
	v_cmp_eq_u32_e32 vcc, 0, v171
	s_waitcnt vmcnt(0)
	s_barrier
	s_and_saveexec_b64 s[2:3], vcc
	s_cbranch_execz .LBB0_518
	s_add_i32 s4, 0, 0x20000
	v_mov_b32_e32 v0, s4
	s_waitcnt vmcnt(0) expcnt(0) lgkmcnt(0)
	ds_read_b32 v2, v0
	s_add_i32 s4, 0, 0x20004
	v_mov_b32_e32 v0, s4
	ds_read_b32 v0, v0
	s_waitcnt lgkmcnt(1)
	v_cmp_ne_u32_e32 vcc, 0, v2
	s_cbranch_vccnz .LBB0_486
	v_readlane_b32 s6, v246, 48
	v_readlane_b32 s4, v246, 0
	v_readlane_b32 s7, v246, 49
	s_mul_i32 s33, s7, s4
	s_add_u32 s4, s76, 0x280200
	s_addc_u32 s5, s77, 0
	s_mul_i32 s33, s33, s6
	s_add_u32 s6, s76, 0x280400
	s_addc_u32 s7, s77, 0
	s_add_u32 s8, s76, 0x280500
	s_addc_u32 s9, s77, 0
	s_add_u32 s10, s76, 0x280600
	s_addc_u32 s11, s77, 0
	s_add_u32 s12, s76, 0x280700
	s_addc_u32 s13, s77, 0
	s_add_u32 s14, s76, 0x280800
	s_addc_u32 s15, s77, 0
	s_add_u32 s16, s76, 0x280900
	s_addc_u32 s17, s77, 0
	s_add_u32 s18, s76, 0x280a00
	s_addc_u32 s19, s77, 0
	s_add_u32 s20, s76, 0x280b00
	s_addc_u32 s21, s77, 0
	s_add_u32 s22, s76, 0x280c00
	s_addc_u32 s23, s77, 0
	s_add_u32 s24, s76, 0x280d00
	s_addc_u32 s25, s77, 0
	s_add_u32 s26, s76, 0x280e00
	s_addc_u32 s27, s77, 0
	s_add_u32 s28, s76, 0x280f00
	s_addc_u32 s29, s77, 0
	s_add_u32 s30, s76, 0x281000
	s_addc_u32 s31, s77, 0
	s_add_u32 s34, s76, 0x281100
	s_addc_u32 s35, s77, 0
	s_add_u32 s36, s76, 0x281200
	s_addc_u32 s37, s77, 0
	s_add_u32 s38, s76, 0x281300
	s_addc_u32 s39, s77, 0
	s_mov_b32 s46, 1
	v_mov_b32_e32 v16, 0
	s_branch .LBB0_474

.LBB0_523:
	s_cmp_lt_u32 s54, 0x400
	s_cbranch_scc1 .Ldf4b_wd
	s_cmp_eq_u32 s85, 1
	s_cbranch_scc0 .Ldf4b_wd
	s_mov_b32 s85, 0
	v_cmp_eq_u32_e64 s[98:99], 0, v171
	s_nop 1
	s_and_saveexec_b64 s[98:99], s[98:99]
	s_cbranch_execz .Ldf4b_wj
	v_mov_b32_e32 v247, 0x20004
	ds_read_b32 v248, v247
	v_readlane_b32 s96, v246, 1
	v_readlane_b32 s97, v246, 2
	v_mov_b32_e32 v249, 0x3b40
	s_mov_b32 s56, 0
	s_waitcnt lgkmcnt(0)
	v_readfirstlane_b32 s101, v248
	s_nop 3
.Ldf4b_poll:
	global_load_dword v250, v249, s[96:97] sc1
	s_waitcnt vmcnt(0)
	v_readfirstlane_b32 s57, v250
	s_nop 0
	s_cmp_ge_u32 s57, s101
	s_cbranch_scc1 .Ldf4b_ok
	s_sleep 1
	s_add_i32 s56, s56, 1
	s_cmp_lt_u32 s56, 0x40000
	s_cbranch_scc1 .Ldf4b_poll

.Ldf4b_wj:
	s_or_b64 exec, exec, s[98:99]
	s_barrier
.Ldf4b_wd:
	s_ashr_i32 s26, s54, 9
	s_lshl_b32 s90, s26, 1
	s_lshr_b32 s21, 16, s90
	s_and_b32 s20, s54, 15
	s_sub_i32 s22, 4, s90
	s_add_i32 s21, s21, -1
	s_bfe_u32 s33, s54, 0x30004
	s_lshr_b32 s22, s20, s22
	s_and_b32 s20, s21, s20
	s_lshl_b32 s27, s20, 8
	s_and_b32 s20, s54, 0xfffffe00
	s_lshl_b32 s21, s33, 6
	s_or_b32 s28, s21, s20
	s_lshl_b32 s20, s54, 5
	s_and_b32 s20, s20, 0x3000
	s_ashr_i32 s29, s28, 31
	s_lshr_b32 s88, 0x1000, s90
	s_sub_i32 s89, s27, 64
	s_or_b32 s91, s22, s20
	v_mov_b32_e32 v1, s29
	v_or_b32_e32 v0, s28, v60
	s_mov_b64 s[40:41], 0
	v_mov_b32_e32 v2, v122
	v_mov_b32_e32 v3, v121
	s_waitcnt vmcnt(0)
	s_barrier
